# HGRN scan step: single dpp add instead of dpp-mov plus masked add; dot product accumulated as one fma chain (drops two packed adds per step, f32 reassociation only)
# speedup vs baseline: 1.0039x; 1.0036x over previous
; #define HG_LD(X, tl_) do { const float* f_ = sF + (tl_) * 128 + seg * 4; const float* q_ = sQ + (tl_) * 128 + seg * 4;   \
;                 X##f0 = *(const f32x4*)(f_); X##f1 = *(const f32x4*)(f_ + 64); X##q0 = *(const f32x4*)(q_); X##q1 = *(const f32x4*)(q_ + 64); \
;                 X##va = sDV[(tl_) * 64 + cp]; X##vb = sDV[(tl_) * 64 + 32 + cp]; } while (0)
; __device__ __forceinline__ void phase_hgrn(KP P, int l_, unsigned char* shm) {
;     ...
;             {
;                 f32x4 Af0, Af1, Aq0, Aq1; float Ava, Avb;
;                 f32x4 Bf0, Bf1, Bq0, Bq1; float Bva, Bvb;
;                 HG_LD(A, 0);
; #pragma unroll 2
;                 for (int tl = 0; tl < T; tl += 2) {
;                     HG_LD(B, tl + 1);
;                     HG_STEP(A, tl);
;                     HG_LD(A, tl + 2);
;                     HG_STEP(B, tl + 1);
;                 }
.LBB0_2164:
	ds_read_b128 v[34:37], v129
	ds_read_b128 v[30:33], v129 offset:256
	ds_read_b128 v[26:29], v129 offset:16384
	ds_read_b128 v[22:25], v129 offset:16640
	ds_read2_b32 v[80:81], v130 offset1:32
	s_waitcnt lgkmcnt(8)
	v_pk_fma_f32 v[70:71], v[20:21], v[70:71], v[78:79] op_sel_hi:[1,1,0]
	v_pk_fma_f32 v[76:77], v[20:21], v[76:77], v[4:5] op_sel_hi:[1,1,0]
	v_pk_fma_f32 v[64:65], v[18:19], v[64:65], v[78:79] op_sel_hi:[1,1,0]
	v_pk_fma_f32 v[82:83], v[18:19], v[62:63], v[4:5] op_sel_hi:[1,1,0]
	s_waitcnt lgkmcnt(7)
	v_pk_fma_f32 v[68:69], v[14:15], v[68:69], v[78:79] op_sel_hi:[1,1,0]
	v_pk_fma_f32 v[74:75], v[14:15], v[74:75], v[4:5] op_sel_hi:[1,1,0]
	v_pk_fma_f32 v[66:67], v[16:17], v[66:67], v[78:79] op_sel_hi:[1,1,0]
	v_pk_fma_f32 v[72:73], v[16:17], v[72:73], v[4:5] op_sel_hi:[1,1,0]
	s_waitcnt lgkmcnt(6)
	v_pk_mul_f32 v[14:15], v[12:13], v[70:71]
	v_pk_mul_f32 v[12:13], v[12:13], v[76:77]
	v_pk_fma_f32 v[14:15], v[10:11], v[64:65], v[14:15]
	v_pk_fma_f32 v[10:11], v[10:11], v[82:83], v[12:13]
	s_waitcnt lgkmcnt(5)
	v_pk_fma_f32 v[12:13], v[8:9], v[66:67], v[14:15]
	v_pk_fma_f32 v[8:9], v[8:9], v[72:73], v[10:11]
	v_pk_fma_f32 v[12:13], v[6:7], v[68:69], v[12:13]
	v_pk_fma_f32 v[6:7], v[6:7], v[74:75], v[8:9]
	v_add_f32_e32 v4, v12, v13
	v_add_f32_e32 v6, v6, v7
	s_nop 0
	v_add_f32_dpp v4, v4, v4 quad_perm:[1,0,3,2] row_mask:0xf bank_mask:0xf bound_ctrl:1
	v_add_f32_dpp v6, v6, v6 quad_perm:[1,0,3,2] row_mask:0xf bank_mask:0xf bound_ctrl:1
	s_nop 0
	v_add_f32_dpp v4, v4, v4 quad_perm:[2,3,0,1] row_mask:0xf bank_mask:0xf bound_ctrl:1
	v_add_f32_dpp v6, v6, v6 quad_perm:[2,3,0,1] row_mask:0xf bank_mask:0xf bound_ctrl:1
	s_and_saveexec_b64 s[22:23], s[8:9]
	s_cbranch_execz .LBB0_2166
	ds_write_b32 v132, v4
	ds_write_b32 v131, v6
.LBB0_2166:
	s_or_b64 exec, exec, s[22:23]
	s_waitcnt lgkmcnt(2)
	v_mov_b32_e32 v4, v81
	ds_read_b128 v[18:21], v129 offset:512
	ds_read_b128 v[14:17], v129 offset:768
	ds_read_b128 v[10:13], v129 offset:16896
	ds_read_b128 v[6:9], v129 offset:17152
	ds_read2_b32 v[62:63], v130 offset0:64 offset1:96
	v_pk_fma_f32 v[70:71], v[70:71], v[36:37], v[80:81] op_sel_hi:[1,1,0]
	v_pk_fma_f32 v[76:77], v[36:37], v[76:77], v[4:5] op_sel_hi:[1,1,0]
	v_pk_fma_f32 v[64:65], v[64:65], v[34:35], v[80:81] op_sel_hi:[1,1,0]
	v_pk_fma_f32 v[78:79], v[34:35], v[82:83], v[4:5] op_sel_hi:[1,1,0]
	v_pk_fma_f32 v[82:83], v[68:69], v[30:31], v[80:81] op_sel_hi:[1,1,0]
	v_pk_fma_f32 v[84:85], v[74:75], v[30:31], v[4:5] op_sel_hi:[1,1,0]
	v_pk_fma_f32 v[86:87], v[66:67], v[32:33], v[80:81] op_sel_hi:[1,1,0]
	v_pk_fma_f32 v[88:89], v[72:73], v[32:33], v[4:5] op_sel_hi:[1,1,0]
	v_pk_mul_f32 v[30:31], v[28:29], v[70:71]
	v_pk_mul_f32 v[28:29], v[28:29], v[76:77]
	v_pk_fma_f32 v[30:31], v[26:27], v[64:65], v[30:31]
	v_pk_fma_f32 v[26:27], v[26:27], v[78:79], v[28:29]
	v_pk_fma_f32 v[28:29], v[24:25], v[86:87], v[30:31]
	v_pk_fma_f32 v[24:25], v[24:25], v[88:89], v[26:27]
	v_pk_fma_f32 v[28:29], v[22:23], v[82:83], v[28:29]
	v_pk_fma_f32 v[22:23], v[22:23], v[84:85], v[24:25]
	v_add_f32_e32 v4, v28, v29
	v_add_f32_e32 v22, v22, v23
	s_nop 0
	v_add_f32_dpp v4, v4, v4 quad_perm:[1,0,3,2] row_mask:0xf bank_mask:0xf bound_ctrl:1
	v_add_f32_dpp v22, v22, v22 quad_perm:[1,0,3,2] row_mask:0xf bank_mask:0xf bound_ctrl:1
	s_nop 0
	v_add_f32_dpp v4, v4, v4 quad_perm:[2,3,0,1] row_mask:0xf bank_mask:0xf bound_ctrl:1
	v_add_f32_dpp v22, v22, v22 quad_perm:[2,3,0,1] row_mask:0xf bank_mask:0xf bound_ctrl:1
	s_and_saveexec_b64 s[22:23], s[8:9]
	s_cbranch_execz .LBB0_2168
	ds_write_b32 v132, v4 offset:1024
	ds_write_b32 v131, v22 offset:1024
; #define HG_LD(X, tl_) do { const float* f_ = sF + (tl_) * 128 + seg * 4; const float* q_ = sQ + (tl_) * 128 + seg * 4;   \
;                 X##f0 = *(const f32x4*)(f_); X##f1 = *(const f32x4*)(f_ + 64); X##q0 = *(const f32x4*)(q_); X##q1 = *(const f32x4*)(q_ + 64); \
;                 X##va = sDV[(tl_) * 64 + cp]; X##vb = sDV[(tl_) * 64 + 32 + cp]; } while (0)
; __device__ __forceinline__ void phase_hgrn(KP P, int l_, unsigned char* shm) {
;     ...
;             {
;                 f32x4 Af0, Af1, Aq0, Aq1; float Ava, Avb;
;                 f32x4 Bf0, Bf1, Bq0, Bq1; float Bva, Bvb;
;                 HG_LD(A, 0);
; #pragma unroll 2
;                 for (int tl = 0; tl < T; tl += 2) {
;                     HG_LD(B, tl + 1);
;                     HG_STEP(A, tl);
;                     HG_LD(A, tl + 2);
;                     HG_STEP(B, tl + 1);
;                 }
.LBB0_2168:
	s_or_b64 exec, exec, s[22:23]
	s_waitcnt lgkmcnt(2)
	v_mov_b32_e32 v4, v63
	ds_read_b128 v[34:37], v129 offset:1024
	ds_read_b128 v[30:33], v129 offset:1280
	ds_read_b128 v[26:29], v129 offset:17408
	ds_read_b128 v[22:25], v129 offset:17664
	ds_read2_b32 v[66:67], v130 offset0:128 offset1:160
	v_pk_fma_f32 v[70:71], v[20:21], v[70:71], v[62:63] op_sel_hi:[1,1,0]
	v_pk_fma_f32 v[72:73], v[20:21], v[76:77], v[4:5] op_sel_hi:[1,1,0]
	v_pk_fma_f32 v[64:65], v[18:19], v[64:65], v[62:63] op_sel_hi:[1,1,0]
	v_pk_fma_f32 v[68:69], v[18:19], v[78:79], v[4:5] op_sel_hi:[1,1,0]
	v_pk_fma_f32 v[74:75], v[14:15], v[82:83], v[62:63] op_sel_hi:[1,1,0]
	v_pk_fma_f32 v[80:81], v[14:15], v[84:85], v[4:5] op_sel_hi:[1,1,0]
	v_pk_fma_f32 v[82:83], v[16:17], v[86:87], v[62:63] op_sel_hi:[1,1,0]
	v_pk_fma_f32 v[84:85], v[16:17], v[88:89], v[4:5] op_sel_hi:[1,1,0]
	v_pk_mul_f32 v[14:15], v[12:13], v[70:71]
	v_pk_mul_f32 v[12:13], v[12:13], v[72:73]
	v_pk_fma_f32 v[14:15], v[10:11], v[64:65], v[14:15]
	v_pk_fma_f32 v[10:11], v[10:11], v[68:69], v[12:13]
	v_pk_fma_f32 v[12:13], v[8:9], v[82:83], v[14:15]
	v_pk_fma_f32 v[8:9], v[8:9], v[84:85], v[10:11]
	v_pk_fma_f32 v[12:13], v[6:7], v[74:75], v[12:13]
	v_pk_fma_f32 v[6:7], v[6:7], v[80:81], v[8:9]
	v_add_f32_e32 v4, v12, v13
	v_add_f32_e32 v6, v6, v7
	s_nop 0
	v_add_f32_dpp v4, v4, v4 quad_perm:[1,0,3,2] row_mask:0xf bank_mask:0xf bound_ctrl:1
	v_add_f32_dpp v6, v6, v6 quad_perm:[1,0,3,2] row_mask:0xf bank_mask:0xf bound_ctrl:1
	s_nop 0
	v_add_f32_dpp v4, v4, v4 quad_perm:[2,3,0,1] row_mask:0xf bank_mask:0xf bound_ctrl:1
	v_add_f32_dpp v6, v6, v6 quad_perm:[2,3,0,1] row_mask:0xf bank_mask:0xf bound_ctrl:1
	s_and_saveexec_b64 s[22:23], s[8:9]
	s_cbranch_execz .LBB0_2170
	ds_write_b32 v132, v4 offset:2048
	ds_write_b32 v131, v6 offset:2048
.LBB0_2170:
	s_or_b64 exec, exec, s[22:23]
	s_waitcnt lgkmcnt(2)
	v_mov_b32_e32 v86, v67
	v_pk_fma_f32 v[70:71], v[70:71], v[36:37], v[66:67] op_sel_hi:[1,1,0]
	v_pk_fma_f32 v[76:77], v[36:37], v[72:73], v[86:87] op_sel_hi:[1,1,0]
	v_pk_fma_f32 v[64:65], v[64:65], v[34:35], v[66:67] op_sel_hi:[1,1,0]
	v_pk_fma_f32 v[62:63], v[34:35], v[68:69], v[86:87] op_sel_hi:[1,1,0]
	v_pk_fma_f32 v[68:69], v[74:75], v[30:31], v[66:67] op_sel_hi:[1,1,0]
	v_pk_fma_f32 v[74:75], v[80:81], v[30:31], v[86:87] op_sel_hi:[1,1,0]
	v_pk_fma_f32 v[66:67], v[82:83], v[32:33], v[66:67] op_sel_hi:[1,1,0]
	v_pk_fma_f32 v[72:73], v[84:85], v[32:33], v[86:87] op_sel_hi:[1,1,0]
	v_pk_mul_f32 v[30:31], v[28:29], v[70:71]
	v_pk_mul_f32 v[28:29], v[28:29], v[76:77]
	v_pk_fma_f32 v[30:31], v[26:27], v[64:65], v[30:31]
	v_pk_fma_f32 v[26:27], v[26:27], v[62:63], v[28:29]
	v_pk_fma_f32 v[28:29], v[24:25], v[66:67], v[30:31]
	v_pk_fma_f32 v[24:25], v[24:25], v[72:73], v[26:27]
	v_pk_fma_f32 v[28:29], v[22:23], v[68:69], v[28:29]
	v_pk_fma_f32 v[22:23], v[22:23], v[74:75], v[24:25]
	v_add_f32_e32 v24, v28, v29
	v_add_f32_e32 v23, v22, v23
	ds_read2_b32 v[78:79], v130 offset0:192 offset1:224
	ds_read_b128 v[18:21], v129 offset:1536
	ds_read_b128 v[14:17], v129 offset:1792
	ds_read_b128 v[10:13], v129 offset:17920
	ds_read_b128 v[6:9], v129 offset:18176
	v_add_f32_dpp v22, v24, v24 quad_perm:[1,0,3,2] row_mask:0xf bank_mask:0xf bound_ctrl:1
	v_add_f32_dpp v23, v23, v23 quad_perm:[1,0,3,2] row_mask:0xf bank_mask:0xf bound_ctrl:1
	s_waitcnt lgkmcnt(4)
	v_mov_b32_e32 v4, v79
	v_add_f32_dpp v22, v22, v22 quad_perm:[2,3,0,1] row_mask:0xf bank_mask:0xf bound_ctrl:1
	v_add_f32_dpp v23, v23, v23 quad_perm:[2,3,0,1] row_mask:0xf bank_mask:0xf bound_ctrl:1
	s_and_saveexec_b64 s[22:23], s[8:9]
	s_cbranch_execz .LBB0_2163
	ds_write_b32 v132, v22 offset:3072
	ds_write_b32 v131, v23 offset:3072
	s_branch .LBB0_2163
